# MLP-in epilogue: H stores without sc1 (write-back) under slab layout + XCC-local barriers; rest identical to v34
# speedup vs baseline: 1.0152x; 1.0119x over previous
; __device__ __forceinline__ unsigned cvt_pk_bf16(float lo, float hi) { f32x2 v = {lo, hi}; bf16x2_t b = __builtin_convertvector(v, bf16x2_t); return __builtin_bit_cast(unsigned, b); }
;     __device__ __forceinline__ void operator()(const f32x4 (&acc)[2][2][4][2], const Unit& u, int wr, int wc, int fr, int fq) const {
;     ...
;                 if (MODE == 0 || MODE == 1) {
; #pragma unroll
;                     for (int bj = 0; bj < 2; ++bj) {
;                         const int hf = 2 * u.pn + bj;
;                         bf16_t* dst;
;                         if (split2) dst = ((hf & 1) ? O2 : O) + (size_t)row * ldc + (hf >> 1) * 128 + wc * 32 + 8 * fq;
;                         else dst = O + (size_t)row * ldc + hf * 128 + wc * 32 + 8 * fq;
;                         f32x4 v0 = acc[ai][bj][m][0] * sc, v1 = acc[ai][bj][m][1] * sc;
;                         if (MODE == 1) {
; #pragma unroll
;                             for (int e = 0; e < 4; ++e) { float a = fmaxf(v0[e], 0.f), b = fmaxf(v1[e], 0.f); v0[e] = a * a; v1[e] = b * b; }
;                         }
;                         u32x4 w; w.x = cvt_pk_bf16(v0[0], v0[1]); w.y = cvt_pk_bf16(v0[2], v0[3]); w.z = cvt_pk_bf16(v1[0], v1[1]); w.w = cvt_pk_bf16(v1[2], v1[3]);
;                         if (MODE == 1) asm volatile("global_store_dwordx4 %0, %1, off sc1\n\ts_nop 1" :: "v"(dst), "v"(w) : "memory");
;                         else *(u32x4*)dst = w;
;                     }
.LBB0_1070:
	v_lshl_add_u32 v142, s46, 8, v144
	s_lshl_b32 s6, s44, 8
	v_ashrrev_i32_e32 v143, 31, v142
	v_max_f32_e32 v120, 0, v120
	v_max_f32_e32 v121, 0, v121
	v_lshlrev_b64 v[140:141], 13, v[142:143]
	s_ashr_i32 s7, s6, 31
	v_pk_mul_f32 v[148:149], v[120:121], v[120:121]
	v_lshl_add_u64 v[140:141], s[88:89], 0, v[140:141]
	s_lshl_b64 s[6:7], s[6:7], 1
	v_max_f32_e32 v122, 0, v122
	v_max_f32_e32 v123, 0, v123
	v_lshl_add_u64 v[140:141], v[140:141], 0, s[6:7]
	v_max_f32_e32 v124, 0, v124
	v_max_f32_e32 v125, 0, v125
	v_max_f32_e32 v120, 0, v126
	v_max_f32_e32 v121, 0, v127
	v_pk_mul_f32 v[150:151], v[122:123], v[122:123]
	v_lshl_add_u64 v[140:141], v[140:141], 0, s[50:51]
	v_pk_mul_f32 v[124:125], v[124:125], v[124:125]
	v_pk_mul_f32 v[126:127], v[120:121], v[120:121]
	v_cvt_pk_bf16_f32 v122, v148, v149
	v_cvt_pk_bf16_f32 v123, v150, v151
	v_max_f32_e32 v112, 0, v112
	v_max_f32_e32 v113, 0, v113
	v_lshl_add_u64 v[140:141], v[140:141], 0, v[180:181]
	v_cvt_pk_bf16_f32 v120, v124, v125
	v_cvt_pk_bf16_f32 v121, v126, v127
	global_store_dwordx4 v[140:141], v[120:123], off
	s_nop 1
	v_pk_mul_f32 v[122:123], v[112:113], v[112:113]
	v_max_f32_e32 v116, 0, v116
	v_max_f32_e32 v117, 0, v117
	v_max_f32_e32 v114, 0, v114
	v_pk_mul_f32 v[116:117], v[116:117], v[116:117]
	v_max_f32_e32 v112, 0, v118
	v_max_f32_e32 v113, 0, v119
	v_max_f32_e32 v115, 0, v115
	s_mov_b64 s[26:27], 0x100
	v_pk_mul_f32 v[118:119], v[112:113], v[112:113]
	v_pk_mul_f32 v[124:125], v[114:115], v[114:115]
	v_cvt_pk_bf16_f32 v112, v116, v117
	v_lshl_add_u64 v[120:121], v[140:141], 0, s[26:27]
	v_cvt_pk_bf16_f32 v113, v118, v119
	v_cvt_pk_bf16_f32 v114, v122, v123
	v_cvt_pk_bf16_f32 v115, v124, v125
	global_store_dwordx4 v[120:121], v[112:115], off
	s_nop 1
	v_or_b32_e32 v112, 16, v142
	v_ashrrev_i32_e32 v113, 31, v112
	v_max_f32_e32 v104, 0, v104
	v_max_f32_e32 v105, 0, v105
	v_lshlrev_b64 v[112:113], 13, v[112:113]
	v_pk_mul_f32 v[114:115], v[104:105], v[104:105]
	v_lshl_add_u64 v[112:113], s[88:89], 0, v[112:113]
	v_max_f32_e32 v106, 0, v106
	v_max_f32_e32 v107, 0, v107
	v_lshl_add_u64 v[112:113], v[112:113], 0, s[6:7]
	v_max_f32_e32 v108, 0, v108
	v_max_f32_e32 v109, 0, v109
	v_max_f32_e32 v104, 0, v110
	v_max_f32_e32 v105, 0, v111
	v_pk_mul_f32 v[116:117], v[106:107], v[106:107]
	v_lshl_add_u64 v[112:113], v[112:113], 0, s[50:51]
	v_pk_mul_f32 v[108:109], v[108:109], v[108:109]
	v_pk_mul_f32 v[110:111], v[104:105], v[104:105]
	v_cvt_pk_bf16_f32 v106, v114, v115
	v_cvt_pk_bf16_f32 v107, v116, v117
	v_max_f32_e32 v96, 0, v96
	v_max_f32_e32 v97, 0, v97
	v_lshl_add_u64 v[112:113], v[112:113], 0, v[180:181]
	v_cvt_pk_bf16_f32 v104, v108, v109
	v_cvt_pk_bf16_f32 v105, v110, v111
	global_store_dwordx4 v[112:113], v[104:107], off
	s_nop 1
	v_pk_mul_f32 v[106:107], v[96:97], v[96:97]
	v_max_f32_e32 v100, 0, v100
	v_max_f32_e32 v101, 0, v101
	v_max_f32_e32 v98, 0, v98
	v_pk_mul_f32 v[100:101], v[100:101], v[100:101]
	v_max_f32_e32 v96, 0, v102
	v_max_f32_e32 v97, 0, v103
	v_max_f32_e32 v99, 0, v99
	v_pk_mul_f32 v[102:103], v[96:97], v[96:97]
	v_pk_mul_f32 v[108:109], v[98:99], v[98:99]
	v_cvt_pk_bf16_f32 v96, v100, v101
	v_lshl_add_u64 v[104:105], v[112:113], 0, s[26:27]
	v_cvt_pk_bf16_f32 v97, v102, v103
	v_cvt_pk_bf16_f32 v98, v106, v107
	v_cvt_pk_bf16_f32 v99, v108, v109
	global_store_dwordx4 v[104:105], v[96:99], off
	s_nop 1
	v_or_b32_e32 v96, 32, v142
	v_ashrrev_i32_e32 v97, 31, v96
	v_max_f32_e32 v88, 0, v88
	v_max_f32_e32 v89, 0, v89
	v_lshlrev_b64 v[96:97], 13, v[96:97]
	v_pk_mul_f32 v[98:99], v[88:89], v[88:89]
	v_lshl_add_u64 v[96:97], s[88:89], 0, v[96:97]
	v_max_f32_e32 v90, 0, v90
	v_max_f32_e32 v91, 0, v91
	v_lshl_add_u64 v[96:97], v[96:97], 0, s[6:7]
	v_max_f32_e32 v92, 0, v92
	v_max_f32_e32 v93, 0, v93
	v_max_f32_e32 v88, 0, v94
	v_max_f32_e32 v89, 0, v95
	v_pk_mul_f32 v[100:101], v[90:91], v[90:91]
	v_lshl_add_u64 v[96:97], v[96:97], 0, s[50:51]
	v_pk_mul_f32 v[92:93], v[92:93], v[92:93]
	v_pk_mul_f32 v[94:95], v[88:89], v[88:89]
	v_cvt_pk_bf16_f32 v90, v98, v99
	v_cvt_pk_bf16_f32 v91, v100, v101
	v_max_f32_e32 v80, 0, v80
	v_max_f32_e32 v81, 0, v81
	v_lshl_add_u64 v[96:97], v[96:97], 0, v[180:181]
	v_cvt_pk_bf16_f32 v88, v92, v93
	v_cvt_pk_bf16_f32 v89, v94, v95
	global_store_dwordx4 v[96:97], v[88:91], off
	s_nop 1
	v_pk_mul_f32 v[90:91], v[80:81], v[80:81]
	v_max_f32_e32 v84, 0, v84
	v_max_f32_e32 v85, 0, v85
	v_max_f32_e32 v82, 0, v82
	v_pk_mul_f32 v[84:85], v[84:85], v[84:85]
	v_max_f32_e32 v80, 0, v86
	v_max_f32_e32 v81, 0, v87
	v_max_f32_e32 v83, 0, v83
	v_pk_mul_f32 v[86:87], v[80:81], v[80:81]
	v_pk_mul_f32 v[92:93], v[82:83], v[82:83]
	v_cvt_pk_bf16_f32 v80, v84, v85
	v_lshl_add_u64 v[88:89], v[96:97], 0, s[26:27]
	v_cvt_pk_bf16_f32 v81, v86, v87
	v_cvt_pk_bf16_f32 v82, v90, v91
	v_cvt_pk_bf16_f32 v83, v92, v93
	global_store_dwordx4 v[88:89], v[80:83], off
	s_nop 1
	v_or_b32_e32 v80, 48, v142
	v_ashrrev_i32_e32 v81, 31, v80
	v_max_f32_e32 v72, 0, v72
	v_max_f32_e32 v73, 0, v73
	v_lshlrev_b64 v[80:81], 13, v[80:81]
	v_pk_mul_f32 v[82:83], v[72:73], v[72:73]
	v_lshl_add_u64 v[80:81], s[88:89], 0, v[80:81]
	v_max_f32_e32 v74, 0, v74
	v_max_f32_e32 v75, 0, v75
	v_lshl_add_u64 v[80:81], v[80:81], 0, s[6:7]
	v_max_f32_e32 v76, 0, v76
	v_max_f32_e32 v77, 0, v77
	v_max_f32_e32 v72, 0, v78
	v_max_f32_e32 v73, 0, v79
	v_pk_mul_f32 v[84:85], v[74:75], v[74:75]
	v_lshl_add_u64 v[80:81], v[80:81], 0, s[50:51]
	v_pk_mul_f32 v[76:77], v[76:77], v[76:77]
	v_pk_mul_f32 v[78:79], v[72:73], v[72:73]
	v_cvt_pk_bf16_f32 v74, v82, v83
	v_cvt_pk_bf16_f32 v75, v84, v85
	v_max_f32_e32 v64, 0, v64
	v_max_f32_e32 v65, 0, v65
	v_lshl_add_u64 v[80:81], v[80:81], 0, v[180:181]
; __device__ __forceinline__ unsigned cvt_pk_bf16(float lo, float hi) { f32x2 v = {lo, hi}; bf16x2_t b = __builtin_convertvector(v, bf16x2_t); return __builtin_bit_cast(unsigned, b); }
;     __device__ __forceinline__ void operator()(const f32x4 (&acc)[2][2][4][2], const Unit& u, int wr, int wc, int fr, int fq) const {
;     ...
;                 if (MODE == 0 || MODE == 1) {
; #pragma unroll
;                     for (int bj = 0; bj < 2; ++bj) {
;                         const int hf = 2 * u.pn + bj;
;                         bf16_t* dst;
;                         if (split2) dst = ((hf & 1) ? O2 : O) + (size_t)row * ldc + (hf >> 1) * 128 + wc * 32 + 8 * fq;
;                         else dst = O + (size_t)row * ldc + hf * 128 + wc * 32 + 8 * fq;
;                         f32x4 v0 = acc[ai][bj][m][0] * sc, v1 = acc[ai][bj][m][1] * sc;
;                         if (MODE == 1) {
; #pragma unroll
;                             for (int e = 0; e < 4; ++e) { float a = fmaxf(v0[e], 0.f), b = fmaxf(v1[e], 0.f); v0[e] = a * a; v1[e] = b * b; }
;                         }
;                         u32x4 w; w.x = cvt_pk_bf16(v0[0], v0[1]); w.y = cvt_pk_bf16(v0[2], v0[3]); w.z = cvt_pk_bf16(v1[0], v1[1]); w.w = cvt_pk_bf16(v1[2], v1[3]);
;                         if (MODE == 1) asm volatile("global_store_dwordx4 %0, %1, off sc1\n\ts_nop 1" :: "v"(dst), "v"(w) : "memory");
;                         else *(u32x4*)dst = w;
;                     }
	v_cvt_pk_bf16_f32 v72, v76, v77
	v_cvt_pk_bf16_f32 v73, v78, v79
	global_store_dwordx4 v[80:81], v[72:75], off
	s_nop 1
	v_pk_mul_f32 v[74:75], v[64:65], v[64:65]
	v_max_f32_e32 v66, 0, v66
	v_max_f32_e32 v67, 0, v67
	v_max_f32_e32 v68, 0, v68
	v_max_f32_e32 v69, 0, v69
	v_max_f32_e32 v64, 0, v70
	v_max_f32_e32 v65, 0, v71
	v_pk_mul_f32 v[76:77], v[66:67], v[66:67]
	v_pk_mul_f32 v[68:69], v[68:69], v[68:69]
	v_pk_mul_f32 v[70:71], v[64:65], v[64:65]
	v_cvt_pk_bf16_f32 v66, v74, v75
	v_cvt_pk_bf16_f32 v67, v76, v77
	v_max_f32_e32 v56, 0, v56
	v_max_f32_e32 v57, 0, v57
	v_lshl_add_u64 v[72:73], v[80:81], 0, s[26:27]
	v_cvt_pk_bf16_f32 v64, v68, v69
	v_cvt_pk_bf16_f32 v65, v70, v71
	global_store_dwordx4 v[72:73], v[64:67], off
	s_nop 1
	v_pk_mul_f32 v[66:67], v[56:57], v[56:57]
	v_max_f32_e32 v58, 0, v58
	v_max_f32_e32 v59, 0, v59
	v_max_f32_e32 v60, 0, v60
	v_max_f32_e32 v61, 0, v61
	v_max_f32_e32 v56, 0, v62
	v_max_f32_e32 v57, 0, v63
	v_pk_mul_f32 v[68:69], v[58:59], v[58:59]
	s_mov_b64 s[6:7], 0x100000
	v_pk_mul_f32 v[60:61], v[60:61], v[60:61]
	v_pk_mul_f32 v[62:63], v[56:57], v[56:57]
	v_cvt_pk_bf16_f32 v58, v66, v67
	v_cvt_pk_bf16_f32 v59, v68, v69
	v_max_f32_e32 v48, 0, v48
	v_max_f32_e32 v49, 0, v49
	v_lshl_add_u64 v[64:65], v[140:141], 0, s[6:7]
	v_cvt_pk_bf16_f32 v56, v60, v61
	v_cvt_pk_bf16_f32 v57, v62, v63
	global_store_dwordx4 v[64:65], v[56:59], off
	s_nop 1
	v_pk_mul_f32 v[58:59], v[48:49], v[48:49]
	v_max_f32_e32 v50, 0, v50
	v_max_f32_e32 v51, 0, v51
	v_max_f32_e32 v52, 0, v52
	v_max_f32_e32 v53, 0, v53
	v_max_f32_e32 v48, 0, v54
	v_max_f32_e32 v49, 0, v55
	v_pk_mul_f32 v[60:61], v[50:51], v[50:51]
	s_mov_b64 s[6:7], 0x100100
	v_pk_mul_f32 v[52:53], v[52:53], v[52:53]
	v_pk_mul_f32 v[54:55], v[48:49], v[48:49]
	v_cvt_pk_bf16_f32 v50, v58, v59
	v_cvt_pk_bf16_f32 v51, v60, v61
	v_max_f32_e32 v40, 0, v40
	v_max_f32_e32 v41, 0, v41
	v_lshl_add_u64 v[56:57], v[140:141], 0, s[6:7]
	v_cvt_pk_bf16_f32 v48, v52, v53
	v_cvt_pk_bf16_f32 v49, v54, v55
	global_store_dwordx4 v[56:57], v[48:51], off
	s_nop 1
	v_pk_mul_f32 v[50:51], v[40:41], v[40:41]
	v_max_f32_e32 v42, 0, v42
	v_max_f32_e32 v43, 0, v43
	v_max_f32_e32 v44, 0, v44
	v_max_f32_e32 v45, 0, v45
	v_max_f32_e32 v40, 0, v46
	v_max_f32_e32 v41, 0, v47
	v_pk_mul_f32 v[52:53], v[42:43], v[42:43]
	s_mov_b64 s[6:7], 0x120000
	v_pk_mul_f32 v[44:45], v[44:45], v[44:45]
	v_pk_mul_f32 v[46:47], v[40:41], v[40:41]
	v_cvt_pk_bf16_f32 v42, v50, v51
	v_cvt_pk_bf16_f32 v43, v52, v53
	v_max_f32_e32 v32, 0, v32
	v_max_f32_e32 v33, 0, v33
	v_lshl_add_u64 v[48:49], v[140:141], 0, s[6:7]
	v_cvt_pk_bf16_f32 v40, v44, v45
	v_cvt_pk_bf16_f32 v41, v46, v47
	global_store_dwordx4 v[48:49], v[40:43], off
	s_nop 1
	v_pk_mul_f32 v[42:43], v[32:33], v[32:33]
	v_max_f32_e32 v34, 0, v34
	v_max_f32_e32 v35, 0, v35
	v_max_f32_e32 v36, 0, v36
	v_max_f32_e32 v37, 0, v37
	v_max_f32_e32 v32, 0, v38
	v_max_f32_e32 v33, 0, v39
	v_pk_mul_f32 v[44:45], v[34:35], v[34:35]
	s_mov_b64 s[6:7], 0x120100
	v_pk_mul_f32 v[36:37], v[36:37], v[36:37]
	v_pk_mul_f32 v[38:39], v[32:33], v[32:33]
	v_cvt_pk_bf16_f32 v34, v42, v43
	v_cvt_pk_bf16_f32 v35, v44, v45
	v_max_f32_e32 v24, 0, v24
	v_max_f32_e32 v25, 0, v25
	v_lshl_add_u64 v[40:41], v[140:141], 0, s[6:7]
	v_cvt_pk_bf16_f32 v32, v36, v37
	v_cvt_pk_bf16_f32 v33, v38, v39
	global_store_dwordx4 v[40:41], v[32:35], off
	s_nop 1
	v_pk_mul_f32 v[34:35], v[24:25], v[24:25]
	v_max_f32_e32 v26, 0, v26
	v_max_f32_e32 v27, 0, v27
	v_max_f32_e32 v28, 0, v28
	v_max_f32_e32 v29, 0, v29
	v_max_f32_e32 v24, 0, v30
	v_max_f32_e32 v25, 0, v31
	v_pk_mul_f32 v[36:37], v[26:27], v[26:27]
	s_mov_b64 s[6:7], 0x140000
	v_pk_mul_f32 v[28:29], v[28:29], v[28:29]
	v_pk_mul_f32 v[30:31], v[24:25], v[24:25]
	v_cvt_pk_bf16_f32 v26, v34, v35
	v_cvt_pk_bf16_f32 v27, v36, v37
	v_max_f32_e32 v16, 0, v16
	v_max_f32_e32 v17, 0, v17
	v_lshl_add_u64 v[32:33], v[140:141], 0, s[6:7]
	v_cvt_pk_bf16_f32 v24, v28, v29
	v_cvt_pk_bf16_f32 v25, v30, v31
	global_store_dwordx4 v[32:33], v[24:27], off
	s_nop 1
	v_pk_mul_f32 v[26:27], v[16:17], v[16:17]
	v_max_f32_e32 v18, 0, v18
	v_max_f32_e32 v19, 0, v19
	v_max_f32_e32 v20, 0, v20
	v_max_f32_e32 v21, 0, v21
	v_max_f32_e32 v16, 0, v22
	v_max_f32_e32 v17, 0, v23
	v_pk_mul_f32 v[28:29], v[18:19], v[18:19]
	s_mov_b64 s[6:7], 0x140100
	v_pk_mul_f32 v[20:21], v[20:21], v[20:21]
	v_pk_mul_f32 v[22:23], v[16:17], v[16:17]
	v_cvt_pk_bf16_f32 v18, v26, v27
	v_cvt_pk_bf16_f32 v19, v28, v29
	v_max_f32_e32 v8, 0, v8
	v_max_f32_e32 v9, 0, v9
	v_lshl_add_u64 v[24:25], v[140:141], 0, s[6:7]
	v_cvt_pk_bf16_f32 v16, v20, v21
	v_cvt_pk_bf16_f32 v17, v22, v23
	global_store_dwordx4 v[24:25], v[16:19], off
	s_nop 1
	v_pk_mul_f32 v[18:19], v[8:9], v[8:9]
	v_max_f32_e32 v10, 0, v10
	v_max_f32_e32 v11, 0, v11
	v_max_f32_e32 v12, 0, v12
	v_max_f32_e32 v13, 0, v13
	v_max_f32_e32 v8, 0, v14
	v_max_f32_e32 v9, 0, v15
	v_pk_mul_f32 v[20:21], v[10:11], v[10:11]
	s_mov_b64 s[6:7], 0x160000
	v_pk_mul_f32 v[12:13], v[12:13], v[12:13]
	v_pk_mul_f32 v[14:15], v[8:9], v[8:9]
	v_cvt_pk_bf16_f32 v10, v18, v19
	v_cvt_pk_bf16_f32 v11, v20, v21
	v_max_f32_e32 v0, 0, v0
	v_max_f32_e32 v1, 0, v1
	v_lshl_add_u64 v[16:17], v[140:141], 0, s[6:7]
	v_cvt_pk_bf16_f32 v8, v12, v13
	v_cvt_pk_bf16_f32 v9, v14, v15
	global_store_dwordx4 v[16:17], v[8:11], off
	s_nop 1
	v_pk_mul_f32 v[10:11], v[0:1], v[0:1]
	v_max_f32_e32 v2, 0, v2
	v_max_f32_e32 v4, 0, v4
	v_max_f32_e32 v5, 0, v5
	v_max_f32_e32 v0, 0, v6
	v_max_f32_e32 v1, 0, v7
	v_max_f32_e32 v3, 0, v3
	s_mov_b64 s[6:7], 0x160100
	v_pk_mul_f32 v[4:5], v[4:5], v[4:5]
	v_pk_mul_f32 v[6:7], v[0:1], v[0:1]
	v_pk_mul_f32 v[12:13], v[2:3], v[2:3]
	v_lshl_add_u64 v[8:9], v[140:141], 0, s[6:7]
	v_cvt_pk_bf16_f32 v0, v4, v5
	v_cvt_pk_bf16_f32 v1, v6, v7
	v_cvt_pk_bf16_f32 v2, v10, v11
	v_cvt_pk_bf16_f32 v3, v12, v13
	global_store_dwordx4 v[8:9], v[0:3], off
	s_nop 1
	s_andn2_b64 vcc, exec, s[38:39]
	s_mov_b64 s[6:7], -1
	s_cbranch_vccnz .LBB0_1058
	s_andn2_b64 vcc, exec, s[0:1]
	s_cbranch_vccnz .LBB0_1057
	s_barrier
	s_branch .LBB0_1057
